# no setprio + up-projection GEMM loop: LDS-DMA loads of each load segment issued before its ds_reads
# baseline (speedup 1.0000x reference)
.LBB0_217:
	s_add_u32 s26, s24, 0xfffc0080
	s_addc_u32 s27, s25, -1
	s_cmp_eq_u32 s50, 12
	s_cselect_b32 s29, s17, s27
	s_cselect_b32 s28, s46, s26
	s_cselect_b32 s27, s15, s49
	s_cselect_b32 s26, s47, s48
	v_lshl_add_u64 v[214:215], s[24:25], 0, v[136:137]
	s_add_i32 m0, s23, 0xc000
	s_nop 0
	global_load_lds_dwordx4 v[214:215], off
	v_lshl_add_u64 v[214:215], s[24:25], 0, v[138:139]
	s_add_i32 m0, s23, 0xe000
	s_nop 0
	global_load_lds_dwordx4 v[214:215], off
	ds_read_b128 v[144:147], v151
	ds_read_b128 v[154:157], v151 offset:1024
	ds_read_b128 v[158:161], v151 offset:2048
	ds_read_b128 v[162:165], v151 offset:3072
	ds_read_b128 v[166:169], v152
	ds_read_b128 v[170:173], v152 offset:1024
	ds_read_b128 v[174:177], v152 offset:2048
	ds_read_b128 v[178:181], v152 offset:3072
	ds_read_b128 v[182:185], v153
	ds_read_b128 v[186:189], v153 offset:1024
	ds_read_b128 v[190:193], v153 offset:2048
	ds_read_b128 v[194:197], v153 offset:3072
	ds_read_b128 v[198:201], v153 offset:4096
	ds_read_b128 v[202:205], v153 offset:5120
	ds_read_b128 v[206:209], v153 offset:6144
	ds_read_b128 v[210:213], v153 offset:7168
	s_waitcnt vmcnt(8)
	s_waitcnt lgkmcnt(0)
	s_barrier
	s_setprio 0
	s_waitcnt lgkmcnt(0)
	v_mfma_f32_16x16x32_bf16 v[124:127], v[144:147], v[182:185], v[124:127]
	v_mfma_f32_16x16x32_bf16 v[120:123], v[158:161], v[182:185], v[120:123]
	v_mfma_f32_16x16x32_bf16 v[108:111], v[144:147], v[190:193], v[108:111]
	v_mfma_f32_16x16x32_bf16 v[104:107], v[158:161], v[190:193], v[104:107]
	v_mfma_f32_16x16x32_bf16 v[92:95], v[144:147], v[198:201], v[92:95]
	v_mfma_f32_16x16x32_bf16 v[88:91], v[158:161], v[198:201], v[88:91]
	v_mfma_f32_16x16x32_bf16 v[76:79], v[144:147], v[206:209], v[76:79]
	v_mfma_f32_16x16x32_bf16 v[72:75], v[158:161], v[206:209], v[72:75]
	v_mfma_f32_16x16x32_bf16 v[124:127], v[154:157], v[186:189], v[124:127]
	v_mfma_f32_16x16x32_bf16 v[120:123], v[162:165], v[186:189], v[120:123]
	v_mfma_f32_16x16x32_bf16 v[108:111], v[154:157], v[194:197], v[108:111]
	v_mfma_f32_16x16x32_bf16 v[104:107], v[162:165], v[194:197], v[104:107]
	v_mfma_f32_16x16x32_bf16 v[92:95], v[154:157], v[202:205], v[92:95]
	v_mfma_f32_16x16x32_bf16 v[88:91], v[162:165], v[202:205], v[88:91]
	v_mfma_f32_16x16x32_bf16 v[76:79], v[154:157], v[210:213], v[76:79]
	v_mfma_f32_16x16x32_bf16 v[72:75], v[162:165], v[210:213], v[72:75]
	s_setprio 0
	s_setprio 0
	v_mfma_f32_16x16x32_bf16 v[116:119], v[166:169], v[182:185], v[116:119]
	v_mfma_f32_16x16x32_bf16 v[112:115], v[174:177], v[182:185], v[112:115]
	v_mfma_f32_16x16x32_bf16 v[100:103], v[166:169], v[190:193], v[100:103]
	v_mfma_f32_16x16x32_bf16 v[96:99], v[174:177], v[190:193], v[96:99]
	v_mfma_f32_16x16x32_bf16 v[84:87], v[166:169], v[198:201], v[84:87]
	v_mfma_f32_16x16x32_bf16 v[80:83], v[174:177], v[198:201], v[80:83]
	v_mfma_f32_16x16x32_bf16 v[68:71], v[166:169], v[206:209], v[68:71]
	v_mfma_f32_16x16x32_bf16 v[64:67], v[174:177], v[206:209], v[64:67]
	v_mfma_f32_16x16x32_bf16 v[116:119], v[170:173], v[186:189], v[116:119]
	v_mfma_f32_16x16x32_bf16 v[112:115], v[178:181], v[186:189], v[112:115]
	v_mfma_f32_16x16x32_bf16 v[100:103], v[170:173], v[194:197], v[100:103]
	v_mfma_f32_16x16x32_bf16 v[96:99], v[178:181], v[194:197], v[96:99]
	v_mfma_f32_16x16x32_bf16 v[84:87], v[170:173], v[202:205], v[84:87]
	v_mfma_f32_16x16x32_bf16 v[80:83], v[178:181], v[202:205], v[80:83]
	v_mfma_f32_16x16x32_bf16 v[68:71], v[170:173], v[210:213], v[68:71]
	v_mfma_f32_16x16x32_bf16 v[64:67], v[178:181], v[210:213], v[64:67]
	s_setprio 0
	s_barrier
	s_add_i32 s51, s42, s30
	v_lshl_add_u64 v[214:215], s[26:27], 0, v[132:133]
	s_mov_b32 m0, s51
	s_nop 0
	global_load_lds_dwordx4 v[214:215], off
	s_add_i32 m0, s51, 0x2000
	s_add_u32 s52, s26, 0x40000
	v_lshl_add_u64 v[216:217], s[26:27], 0, v[128:129]
	s_addc_u32 s53, s27, 0
	s_add_i32 s51, s43, s30
	global_load_lds_dwordx4 v[216:217], off
	v_lshl_add_u64 v[218:219], s[52:53], 0, v[132:133]
	s_mov_b32 m0, s51
	v_lshl_add_u64 v[220:221], s[28:29], 0, v[130:131]
	global_load_lds_dwordx4 v[218:219], off
	v_lshl_add_u64 v[218:219], s[52:53], 0, v[128:129]
	s_add_i32 m0, s51, 0x2000
	s_nop 0
	global_load_lds_dwordx4 v[218:219], off
	v_lshl_add_u64 v[218:219], s[28:29], 0, v[134:135]
	s_mov_b32 m0, s23
	s_nop 0
	global_load_lds_dwordx4 v[218:219], off
	s_mov_b32 m0, s34
	s_nop 0
	global_load_lds_dwordx4 v[220:221], off
	ds_read_b128 v[182:185], v153 offset:16384
	ds_read_b128 v[186:189], v153 offset:17408
	ds_read_b128 v[190:193], v153 offset:18432
	ds_read_b128 v[194:197], v153 offset:19456
	ds_read_b128 v[198:201], v153 offset:20480
	ds_read_b128 v[202:205], v153 offset:21504
	ds_read_b128 v[206:209], v153 offset:22528
	ds_read_b128 v[210:213], v153 offset:23552
	s_waitcnt vmcnt(8)
	s_waitcnt lgkmcnt(0)
	s_barrier
	s_setprio 0
	s_waitcnt lgkmcnt(0)
	v_mfma_f32_16x16x32_bf16 v[60:63], v[144:147], v[182:185], v[60:63]
	v_mfma_f32_16x16x32_bf16 v[56:59], v[158:161], v[182:185], v[56:59]
	v_mfma_f32_16x16x32_bf16 v[44:47], v[144:147], v[190:193], v[44:47]
	v_mfma_f32_16x16x32_bf16 v[40:43], v[158:161], v[190:193], v[40:43]
	v_mfma_f32_16x16x32_bf16 v[28:31], v[144:147], v[198:201], v[28:31]
	v_mfma_f32_16x16x32_bf16 v[24:27], v[158:161], v[198:201], v[24:27]
	v_mfma_f32_16x16x32_bf16 v[12:15], v[144:147], v[206:209], v[12:15]
	v_mfma_f32_16x16x32_bf16 v[8:11], v[158:161], v[206:209], v[8:11]
	v_mfma_f32_16x16x32_bf16 v[60:63], v[154:157], v[186:189], v[60:63]
	v_mfma_f32_16x16x32_bf16 v[56:59], v[162:165], v[186:189], v[56:59]
	v_mfma_f32_16x16x32_bf16 v[44:47], v[154:157], v[194:197], v[44:47]
	v_mfma_f32_16x16x32_bf16 v[40:43], v[162:165], v[194:197], v[40:43]
	v_mfma_f32_16x16x32_bf16 v[28:31], v[154:157], v[202:205], v[28:31]
	v_mfma_f32_16x16x32_bf16 v[24:27], v[162:165], v[202:205], v[24:27]
	v_mfma_f32_16x16x32_bf16 v[12:15], v[154:157], v[210:213], v[12:15]
	v_mfma_f32_16x16x32_bf16 v[8:11], v[162:165], v[210:213], v[8:11]
	s_setprio 0
	s_setprio 0
	v_mfma_f32_16x16x32_bf16 v[52:55], v[166:169], v[182:185], v[52:55]
	v_mfma_f32_16x16x32_bf16 v[48:51], v[174:177], v[182:185], v[48:51]
	v_mfma_f32_16x16x32_bf16 v[36:39], v[166:169], v[190:193], v[36:39]
	v_mfma_f32_16x16x32_bf16 v[32:35], v[174:177], v[190:193], v[32:35]
	v_mfma_f32_16x16x32_bf16 v[20:23], v[166:169], v[198:201], v[20:23]
	v_mfma_f32_16x16x32_bf16 v[16:19], v[174:177], v[198:201], v[16:19]
	v_mfma_f32_16x16x32_bf16 v[4:7], v[166:169], v[206:209], v[4:7]
	v_mfma_f32_16x16x32_bf16 v[0:3], v[174:177], v[206:209], v[0:3]
	v_mfma_f32_16x16x32_bf16 v[52:55], v[170:173], v[186:189], v[52:55]
	v_mfma_f32_16x16x32_bf16 v[48:51], v[178:181], v[186:189], v[48:51]
	v_mfma_f32_16x16x32_bf16 v[36:39], v[170:173], v[194:197], v[36:39]
	v_mfma_f32_16x16x32_bf16 v[32:35], v[178:181], v[194:197], v[32:35]
	v_mfma_f32_16x16x32_bf16 v[20:23], v[170:173], v[202:205], v[20:23]
	v_mfma_f32_16x16x32_bf16 v[16:19], v[178:181], v[202:205], v[16:19]
	v_mfma_f32_16x16x32_bf16 v[4:7], v[170:173], v[210:213], v[4:7]
	v_mfma_f32_16x16x32_bf16 v[0:3], v[178:181], v[210:213], v[0:3]
	s_setprio 0
	s_barrier
	s_add_i32 s51, 0, 0x18000
	s_add_i32 s52, 0, 0x1c000
	v_add_u32_e32 v162, s51, v149
	v_add_u32_e32 v178, s52, v149
	s_add_u32 s28, s28, 0x40000
	s_addc_u32 s29, s29, 0
	s_mov_b32 m0, s35
	v_lshl_add_u64 v[222:223], s[28:29], 0, v[134:135]
	global_load_lds_dwordx4 v[222:223], off
	v_lshl_add_u64 v[222:223], s[28:29], 0, v[130:131]
	s_mov_b32 m0, s36
	s_nop 0
	global_load_lds_dwordx4 v[222:223], off
	ds_read_b128 v[144:147], v162
	ds_read_b128 v[154:157], v162 offset:1024
	ds_read_b128 v[158:161], v162 offset:2048
	ds_read_b128 v[162:165], v162 offset:3072
	ds_read_b128 v[166:169], v178
	ds_read_b128 v[170:173], v178 offset:1024
	ds_read_b128 v[174:177], v178 offset:2048
	ds_read_b128 v[178:181], v178 offset:3072
	ds_read_b128 v[182:185], v153 offset:32768
	ds_read_b128 v[186:189], v153 offset:33792
	ds_read_b128 v[190:193], v153 offset:34816
	ds_read_b128 v[194:197], v153 offset:35840
	ds_read_b128 v[198:201], v153 offset:36864
	ds_read_b128 v[202:205], v153 offset:37888
	ds_read_b128 v[206:209], v153 offset:38912
	ds_read_b128 v[210:213], v153 offset:39936
	s_waitcnt vmcnt(8)
	s_waitcnt lgkmcnt(0)
	s_barrier
	s_setprio 0
	s_waitcnt lgkmcnt(0)
	v_mfma_f32_16x16x32_bf16 v[124:127], v[144:147], v[182:185], v[124:127]
	v_mfma_f32_16x16x32_bf16 v[120:123], v[158:161], v[182:185], v[120:123]
	v_mfma_f32_16x16x32_bf16 v[108:111], v[144:147], v[190:193], v[108:111]
	v_mfma_f32_16x16x32_bf16 v[104:107], v[158:161], v[190:193], v[104:107]
	v_mfma_f32_16x16x32_bf16 v[92:95], v[144:147], v[198:201], v[92:95]
	v_mfma_f32_16x16x32_bf16 v[88:91], v[158:161], v[198:201], v[88:91]
	v_mfma_f32_16x16x32_bf16 v[76:79], v[144:147], v[206:209], v[76:79]
	v_mfma_f32_16x16x32_bf16 v[72:75], v[158:161], v[206:209], v[72:75]
	v_mfma_f32_16x16x32_bf16 v[124:127], v[154:157], v[186:189], v[124:127]
	v_mfma_f32_16x16x32_bf16 v[120:123], v[162:165], v[186:189], v[120:123]
	v_mfma_f32_16x16x32_bf16 v[108:111], v[154:157], v[194:197], v[108:111]
	v_mfma_f32_16x16x32_bf16 v[104:107], v[162:165], v[194:197], v[104:107]
	v_mfma_f32_16x16x32_bf16 v[92:95], v[154:157], v[202:205], v[92:95]
	v_mfma_f32_16x16x32_bf16 v[88:91], v[162:165], v[202:205], v[88:91]
	v_mfma_f32_16x16x32_bf16 v[76:79], v[154:157], v[210:213], v[76:79]
	v_mfma_f32_16x16x32_bf16 v[72:75], v[162:165], v[210:213], v[72:75]
	s_setprio 0
	s_setprio 0
	v_mfma_f32_16x16x32_bf16 v[116:119], v[166:169], v[182:185], v[116:119]
	v_mfma_f32_16x16x32_bf16 v[112:115], v[174:177], v[182:185], v[112:115]
	v_mfma_f32_16x16x32_bf16 v[100:103], v[166:169], v[190:193], v[100:103]
	v_mfma_f32_16x16x32_bf16 v[96:99], v[174:177], v[190:193], v[96:99]
	v_mfma_f32_16x16x32_bf16 v[84:87], v[166:169], v[198:201], v[84:87]
	v_mfma_f32_16x16x32_bf16 v[80:83], v[174:177], v[198:201], v[80:83]
	v_mfma_f32_16x16x32_bf16 v[68:71], v[166:169], v[206:209], v[68:71]
	v_mfma_f32_16x16x32_bf16 v[64:67], v[174:177], v[206:209], v[64:67]
	v_mfma_f32_16x16x32_bf16 v[116:119], v[170:173], v[186:189], v[116:119]
	v_mfma_f32_16x16x32_bf16 v[112:115], v[178:181], v[186:189], v[112:115]
	v_mfma_f32_16x16x32_bf16 v[100:103], v[170:173], v[194:197], v[100:103]
	v_mfma_f32_16x16x32_bf16 v[96:99], v[178:181], v[194:197], v[96:99]
	v_mfma_f32_16x16x32_bf16 v[84:87], v[170:173], v[202:205], v[84:87]
	v_mfma_f32_16x16x32_bf16 v[80:83], v[178:181], v[202:205], v[80:83]
	v_mfma_f32_16x16x32_bf16 v[68:71], v[170:173], v[210:213], v[68:71]
	v_mfma_f32_16x16x32_bf16 v[64:67], v[178:181], v[210:213], v[64:67]
	s_setprio 0
	s_barrier
	s_add_i32 s28, s51, s30
	v_lshl_add_u64 v[214:215], v[214:215], 0, s[10:11]
	s_mov_b32 m0, s28
	s_nop 0
	global_load_lds_dwordx4 v[214:215], off
	s_add_i32 m0, s28, 0x2000
	s_add_u32 s26, s26, 0x40080
	v_lshl_add_u64 v[214:215], v[216:217], 0, s[10:11]
	s_addc_u32 s27, s27, 0
	s_add_i32 s28, s52, s30
	global_load_lds_dwordx4 v[214:215], off
	v_lshl_add_u64 v[214:215], s[26:27], 0, v[132:133]
	s_mov_b32 m0, s28
	s_nop 0
	global_load_lds_dwordx4 v[214:215], off
	v_lshl_add_u64 v[214:215], s[26:27], 0, v[128:129]
	s_add_i32 m0, s28, 0x2000
	s_nop 0
	global_load_lds_dwordx4 v[214:215], off
	v_lshl_add_u64 v[214:215], v[218:219], 0, s[10:11]
	s_mov_b32 m0, s39
	s_nop 0
	global_load_lds_dwordx4 v[214:215], off
	v_lshl_add_u64 v[214:215], v[220:221], 0, s[10:11]
	s_mov_b32 m0, s40
	s_nop 0
	global_load_lds_dwordx4 v[214:215], off
	ds_read_b128 v[182:185], v153 offset:49152
	ds_read_b128 v[186:189], v153 offset:50176
	ds_read_b128 v[190:193], v153 offset:51200
	ds_read_b128 v[194:197], v153 offset:52224
	ds_read_b128 v[198:201], v153 offset:53248
	ds_read_b128 v[202:205], v153 offset:54272
	ds_read_b128 v[206:209], v153 offset:55296
	ds_read_b128 v[210:213], v153 offset:56320
	s_waitcnt vmcnt(8)
	s_waitcnt lgkmcnt(0)
	s_barrier
	s_setprio 0
	s_waitcnt lgkmcnt(0)
	v_mfma_f32_16x16x32_bf16 v[60:63], v[144:147], v[182:185], v[60:63]
	v_mfma_f32_16x16x32_bf16 v[56:59], v[158:161], v[182:185], v[56:59]
	v_mfma_f32_16x16x32_bf16 v[44:47], v[144:147], v[190:193], v[44:47]
	v_mfma_f32_16x16x32_bf16 v[40:43], v[158:161], v[190:193], v[40:43]
	v_mfma_f32_16x16x32_bf16 v[28:31], v[144:147], v[198:201], v[28:31]
	v_mfma_f32_16x16x32_bf16 v[24:27], v[158:161], v[198:201], v[24:27]
	v_mfma_f32_16x16x32_bf16 v[12:15], v[144:147], v[206:209], v[12:15]
	v_mfma_f32_16x16x32_bf16 v[8:11], v[158:161], v[206:209], v[8:11]
	v_mfma_f32_16x16x32_bf16 v[60:63], v[154:157], v[186:189], v[60:63]
	v_mfma_f32_16x16x32_bf16 v[56:59], v[162:165], v[186:189], v[56:59]
	v_mfma_f32_16x16x32_bf16 v[44:47], v[154:157], v[194:197], v[44:47]
	v_mfma_f32_16x16x32_bf16 v[40:43], v[162:165], v[194:197], v[40:43]
	v_mfma_f32_16x16x32_bf16 v[28:31], v[154:157], v[202:205], v[28:31]
	v_mfma_f32_16x16x32_bf16 v[24:27], v[162:165], v[202:205], v[24:27]
	v_mfma_f32_16x16x32_bf16 v[12:15], v[154:157], v[210:213], v[12:15]
	v_mfma_f32_16x16x32_bf16 v[8:11], v[162:165], v[210:213], v[8:11]
	s_setprio 0
	s_setprio 0
	v_mfma_f32_16x16x32_bf16 v[52:55], v[166:169], v[182:185], v[52:55]
	v_mfma_f32_16x16x32_bf16 v[48:51], v[174:177], v[182:185], v[48:51]
	v_mfma_f32_16x16x32_bf16 v[36:39], v[166:169], v[190:193], v[36:39]
	v_mfma_f32_16x16x32_bf16 v[32:35], v[174:177], v[190:193], v[32:35]
	v_mfma_f32_16x16x32_bf16 v[20:23], v[166:169], v[198:201], v[20:23]
	v_mfma_f32_16x16x32_bf16 v[16:19], v[174:177], v[198:201], v[16:19]
	v_mfma_f32_16x16x32_bf16 v[4:7], v[166:169], v[206:209], v[4:7]
	v_mfma_f32_16x16x32_bf16 v[0:3], v[174:177], v[206:209], v[0:3]
	v_mfma_f32_16x16x32_bf16 v[52:55], v[170:173], v[186:189], v[52:55]
	v_mfma_f32_16x16x32_bf16 v[48:51], v[178:181], v[186:189], v[48:51]
	v_mfma_f32_16x16x32_bf16 v[36:39], v[170:173], v[194:197], v[36:39]
	v_mfma_f32_16x16x32_bf16 v[32:35], v[178:181], v[194:197], v[32:35]
	v_mfma_f32_16x16x32_bf16 v[20:23], v[170:173], v[202:205], v[20:23]
	v_mfma_f32_16x16x32_bf16 v[16:19], v[178:181], v[202:205], v[16:19]
	v_mfma_f32_16x16x32_bf16 v[4:7], v[170:173], v[210:213], v[4:7]
	v_mfma_f32_16x16x32_bf16 v[0:3], v[178:181], v[210:213], v[0:3]
	s_setprio 0
	s_barrier
	s_add_i32 s50, s50, 2
	s_add_u32 s24, s24, 0x100
	s_addc_u32 s25, s25, 0
	s_add_u32 s48, s48, 0x100
	s_addc_u32 s49, s49, 0
	s_cmp_gt_u32 s50, 13
	s_cbranch_scc0 .LBB0_217
	s_and_b64 vcc, exec, s[12:13]
	s_cbranch_vccz .LBB0_220
	s_barrier
